# weight transpose (w_in): next 64x64 item loaded into a second register set while the current one is transposed and stored
# speedup vs baseline: 1.0005x; 1.0005x over previous
; #define LAS __attribute__((address_space(3)))
; __device__ __forceinline__ void tr_item(const float* W, int K, int N, bf16_t* WT, int ldk, int split, int shift, LAS float* scr, int item, int lane) {
;     const int nblk = (N + 63) >> 6, kb = item / nblk, nb = item - kb * nblk, k0 = 64 * kb, n0 = 64 * nb;
;     const int c4 = (lane & 15) * 4, rq = lane >> 4;
;     const bool okc = n0 + c4 < N;
;     f32x4 tv[16];
; #pragma unroll
;     for (int i = 0; i < 16; ++i) { const int kk = i * 4 + rq; tv[i] = okc ? *(const f32x4*)(W + (size_t)(k0 + kk) * N + n0 + c4) : (f32x4){0.f, 0.f, 0.f, 0.f}; }
; __device__ __forceinline__ void tr_matrix(const float* W, int K, int N, bf16_t* WT, int ldk, int split, int shift, LAS float* scr, int gw, int ngw, int lane) {
;     const int nitems = (K >> 6) * ((N + 63) >> 6);
;     for (int it = gw; it < nitems; it += ngw) tr_item(W, K, N, WT, ldk, split, shift, scr, it, lane);
.LBB0_7:
	s_and_saveexec_b64 s[24:25], vcc
	s_cbranch_execz .LBB0_58
	s_load_dwordx2 s[14:15], s[20:21], 0x18
	s_mul_i32 s29, s22, 0x8910000
	s_mul_hi_u32 s28, s22, 0x8910000
	v_mad_u64_u32 v[82:83], s[26:27], s22, v105, v[70:71]
	s_waitcnt lgkmcnt(0)
	s_add_u32 s14, s14, s29
	s_addc_u32 s15, s15, s28
	v_lshl_add_u64 v[84:85], s[14:15], 0, v[68:69]
	s_mov_b64 s[26:27], 0
	v_mov_b32_e32 v108, v92
	v_mov_b32_e32 v176, v108
	v_mul_hi_i32 v112, v176, s5
	v_lshrrev_b32_e32 v113, 31, v112
	v_ashrrev_i32_e32 v112, 7, v112
	v_add_u32_e32 v112, v112, v113
	v_mul_i32_i24_e32 v113, 0xfffffeed, v112
	v_add_lshl_u32 v188, v113, v176, 6
	v_lshlrev_b32_e32 v190, 6, v112
	v_or_b32_e32 v112, v188, v66
	v_ashrrev_i32_e32 v189, 31, v188
	v_cmp_gt_i32_e64 s[14:15], s33, v112
	v_or_b32_e32 v191, v190, v93
	v_lshl_add_u64 v[192:193], v[188:189], 2, v[84:85]
	v_mov_b32_e32 v112, 0
	v_mov_b32_e32 v116, 0
	v_mov_b32_e32 v117, 0
	v_mov_b32_e32 v118, 0
	v_mov_b32_e32 v119, 0
	s_and_saveexec_b64 s[28:29], s[14:15]
	s_cbranch_execz .Lmy_wa_12
	v_mad_i64_i32 v[114:115], s[30:31], v191, s36, v[192:193]
	global_load_dwordx4 v[116:119], v[114:115], off
.Lmy_wa_12:
	s_or_b64 exec, exec, s[28:29]
	v_mov_b32_e32 v113, 0
	v_mov_b32_e32 v114, 0
	v_mov_b32_e32 v115, 0
	s_and_saveexec_b64 s[28:29], s[14:15]
	s_cbranch_execz .Lmy_wa_14
	v_or_b32_e32 v112, 4, v191
	v_mad_i64_i32 v[112:113], s[30:31], v112, s36, v[192:193]
	global_load_dwordx4 v[112:115], v[112:113], off
.Lmy_wa_14:
	s_or_b64 exec, exec, s[28:29]
	v_mov_b32_e32 v120, 0
	v_mov_b32_e32 v124, 0
	v_mov_b32_e32 v125, 0
	v_mov_b32_e32 v126, 0
	v_mov_b32_e32 v127, 0
	s_and_saveexec_b64 s[28:29], s[14:15]
	s_cbranch_execz .Lmy_wa_16
	v_or_b32_e32 v121, 8, v191
	v_mad_i64_i32 v[122:123], s[30:31], v121, s36, v[192:193]
	global_load_dwordx4 v[124:127], v[122:123], off
.Lmy_wa_16:
	s_or_b64 exec, exec, s[28:29]
	v_mov_b32_e32 v121, 0
	v_mov_b32_e32 v122, 0
	v_mov_b32_e32 v123, 0
	s_and_saveexec_b64 s[28:29], s[14:15]
	s_cbranch_execz .Lmy_wa_18
	v_or_b32_e32 v120, 12, v191
	v_mad_i64_i32 v[120:121], s[30:31], v120, s36, v[192:193]
	global_load_dwordx4 v[120:123], v[120:121], off
.Lmy_wa_18:
	s_or_b64 exec, exec, s[28:29]
	v_mov_b32_e32 v128, 0
	v_mov_b32_e32 v132, 0
	v_mov_b32_e32 v133, 0
	v_mov_b32_e32 v134, 0
	v_mov_b32_e32 v135, 0
	s_and_saveexec_b64 s[28:29], s[14:15]
	s_cbranch_execz .Lmy_wa_20
	v_or_b32_e32 v129, 16, v191
	v_mad_i64_i32 v[130:131], s[30:31], v129, s36, v[192:193]
	global_load_dwordx4 v[132:135], v[130:131], off
.Lmy_wa_20:
	s_or_b64 exec, exec, s[28:29]
	v_mov_b32_e32 v129, 0
	v_mov_b32_e32 v130, 0
	v_mov_b32_e32 v131, 0
	s_and_saveexec_b64 s[28:29], s[14:15]
	s_cbranch_execz .Lmy_wa_22
	v_or_b32_e32 v128, 20, v191
	v_mad_i64_i32 v[128:129], s[30:31], v128, s36, v[192:193]
	global_load_dwordx4 v[128:131], v[128:129], off
.Lmy_wa_22:
	s_or_b64 exec, exec, s[28:29]
	v_mov_b32_e32 v136, 0
	v_mov_b32_e32 v140, 0
	v_mov_b32_e32 v141, 0
	v_mov_b32_e32 v142, 0
	v_mov_b32_e32 v143, 0
	s_and_saveexec_b64 s[28:29], s[14:15]
	s_cbranch_execz .Lmy_wa_24
	v_or_b32_e32 v137, 24, v191
	v_mad_i64_i32 v[138:139], s[30:31], v137, s36, v[192:193]
	global_load_dwordx4 v[140:143], v[138:139], off
.Lmy_wa_24:
	s_or_b64 exec, exec, s[28:29]
	v_mov_b32_e32 v137, 0
	v_mov_b32_e32 v138, 0
	v_mov_b32_e32 v139, 0
	s_and_saveexec_b64 s[28:29], s[14:15]
	s_cbranch_execz .Lmy_wa_26
	v_or_b32_e32 v136, 28, v191
	v_mad_i64_i32 v[136:137], s[30:31], v136, s36, v[192:193]
	global_load_dwordx4 v[136:139], v[136:137], off
.Lmy_wa_26:
	s_or_b64 exec, exec, s[28:29]
	v_mov_b32_e32 v144, 0
	v_mov_b32_e32 v148, 0
	v_mov_b32_e32 v149, 0
	v_mov_b32_e32 v150, 0
	v_mov_b32_e32 v151, 0
	s_and_saveexec_b64 s[28:29], s[14:15]
	s_cbranch_execz .Lmy_wa_28
	v_or_b32_e32 v145, 32, v191
	v_mad_i64_i32 v[146:147], s[30:31], v145, s36, v[192:193]
	global_load_dwordx4 v[148:151], v[146:147], off
.Lmy_wa_28:
	s_or_b64 exec, exec, s[28:29]
	v_mov_b32_e32 v145, 0
	v_mov_b32_e32 v146, 0
	v_mov_b32_e32 v147, 0
	s_and_saveexec_b64 s[28:29], s[14:15]
	s_cbranch_execz .Lmy_wa_30
	v_or_b32_e32 v144, 36, v191
	v_mad_i64_i32 v[144:145], s[30:31], v144, s36, v[192:193]
	global_load_dwordx4 v[144:147], v[144:145], off
.Lmy_wa_30:
	s_or_b64 exec, exec, s[28:29]
	v_mov_b32_e32 v152, 0
	v_mov_b32_e32 v156, 0
	v_mov_b32_e32 v157, 0
	v_mov_b32_e32 v158, 0
	v_mov_b32_e32 v159, 0
	s_and_saveexec_b64 s[28:29], s[14:15]
	s_cbranch_execz .Lmy_wa_32
	v_or_b32_e32 v153, 40, v191
	v_mad_i64_i32 v[154:155], s[30:31], v153, s36, v[192:193]
	global_load_dwordx4 v[156:159], v[154:155], off
.Lmy_wa_32:
	s_or_b64 exec, exec, s[28:29]
	v_mov_b32_e32 v153, 0
	v_mov_b32_e32 v154, 0
	v_mov_b32_e32 v155, 0
	s_and_saveexec_b64 s[28:29], s[14:15]
	s_cbranch_execz .Lmy_wa_34
	v_or_b32_e32 v152, 44, v191
	v_mad_i64_i32 v[152:153], s[30:31], v152, s36, v[192:193]
	global_load_dwordx4 v[152:155], v[152:153], off
.Lmy_wa_34:
	s_or_b64 exec, exec, s[28:29]
	v_mov_b32_e32 v160, 0
	v_mov_b32_e32 v164, 0
	v_mov_b32_e32 v165, 0
	v_mov_b32_e32 v166, 0
	v_mov_b32_e32 v167, 0
	s_and_saveexec_b64 s[28:29], s[14:15]
	s_cbranch_execz .Lmy_wa_36
	v_or_b32_e32 v161, 48, v191
	v_mad_i64_i32 v[162:163], s[30:31], v161, s36, v[192:193]
	global_load_dwordx4 v[164:167], v[162:163], off
.Lmy_wa_36:
	s_or_b64 exec, exec, s[28:29]
	v_mov_b32_e32 v161, 0
	v_mov_b32_e32 v162, 0
	v_mov_b32_e32 v163, 0
	s_and_saveexec_b64 s[28:29], s[14:15]
	s_cbranch_execz .Lmy_wa_38
	v_or_b32_e32 v160, 52, v191
	v_mad_i64_i32 v[160:161], s[30:31], v160, s36, v[192:193]
	global_load_dwordx4 v[160:163], v[160:161], off
.Lmy_wa_38:
	s_or_b64 exec, exec, s[28:29]
	v_mov_b32_e32 v168, 0
	v_mov_b32_e32 v172, 0
	v_mov_b32_e32 v173, 0
	v_mov_b32_e32 v174, 0
	v_mov_b32_e32 v175, 0
	s_and_saveexec_b64 s[28:29], s[14:15]
	s_cbranch_execz .Lmy_wa_40
	v_or_b32_e32 v169, 56, v191
	v_mad_i64_i32 v[170:171], s[30:31], v169, s36, v[192:193]
	global_load_dwordx4 v[172:175], v[170:171], off
.Lmy_wa_40:
	s_or_b64 exec, exec, s[28:29]
	v_mov_b32_e32 v169, 0
	v_mov_b32_e32 v170, 0
	v_mov_b32_e32 v171, 0
	s_and_saveexec_b64 s[28:29], s[14:15]
	s_cbranch_execz .Lmy_wa_42
	v_or_b32_e32 v168, 60, v191
	v_mad_i64_i32 v[168:169], s[14:15], v168, s36, v[192:193]
	global_load_dwordx4 v[168:171], v[168:169], off
.Lmy_wa_42:
	s_or_b64 exec, exec, s[28:29]
	s_waitcnt vmcnt(0)
	s_branch .LBB0_10

; __device__ __forceinline__ void tr_item(const float* W, int K, int N, bf16_t* WT, int ldk, int split, int shift, LAS float* scr, int item, int lane) {
;     const int nblk = (N + 63) >> 6, kb = item / nblk, nb = item - kb * nblk, k0 = 64 * kb, n0 = 64 * nb;
;     const int c4 = (lane & 15) * 4, rq = lane >> 4;
;     const bool okc = n0 + c4 < N;
;     f32x4 tv[16];
; #pragma unroll
;     for (int i = 0; i < 16; ++i) { const int kk = i * 4 + rq; tv[i] = okc ? *(const f32x4*)(W + (size_t)(k0 + kk) * N + n0 + c4) : (f32x4){0.f, 0.f, 0.f, 0.f}; }
.LBB0_10:
	v_mul_hi_i32 v2, v108, s5
	v_lshrrev_b32_e32 v3, 31, v2
	v_ashrrev_i32_e32 v2, 7, v2
	v_add_u32_e32 v2, v2, v3
	v_mul_i32_i24_e32 v3, 0xfffffeed, v2
	v_add_lshl_u32 v86, v3, v108, 6
	v_lshlrev_b32_e32 v88, 6, v2
	v_or_b32_e32 v2, v86, v66
	v_ashrrev_i32_e32 v87, 31, v86
	v_cmp_gt_i32_e64 s[14:15], s33, v2
	v_or_b32_e32 v89, v88, v93
	v_lshl_add_u64 v[90:91], v[86:87], 2, v[84:85]
	s_waitcnt vmcnt(0)
	v_mov_b32_e32 v2, v112
	v_mov_b32_e32 v3, v113
	v_mov_b32_e32 v4, v114
	v_mov_b32_e32 v5, v115
	v_mov_b32_e32 v6, v116
	v_mov_b32_e32 v7, v117
	v_mov_b32_e32 v8, v118
	v_mov_b32_e32 v9, v119
	v_mov_b32_e32 v10, v120
	v_mov_b32_e32 v11, v121
	v_mov_b32_e32 v12, v122
	v_mov_b32_e32 v13, v123
	v_mov_b32_e32 v14, v124
	v_mov_b32_e32 v15, v125
	v_mov_b32_e32 v16, v126
	v_mov_b32_e32 v17, v127
	v_mov_b32_e32 v18, v128
	v_mov_b32_e32 v19, v129
	v_mov_b32_e32 v20, v130
	v_mov_b32_e32 v21, v131
	v_mov_b32_e32 v22, v132
	v_mov_b32_e32 v23, v133
	v_mov_b32_e32 v24, v134
	v_mov_b32_e32 v25, v135
	v_mov_b32_e32 v26, v136
	v_mov_b32_e32 v27, v137
	v_mov_b32_e32 v28, v138
	v_mov_b32_e32 v29, v139
	v_mov_b32_e32 v30, v140
	v_mov_b32_e32 v31, v141
	v_mov_b32_e32 v32, v142
	v_mov_b32_e32 v33, v143
	v_mov_b32_e32 v34, v144
	v_mov_b32_e32 v35, v145
	v_mov_b32_e32 v36, v146
	v_mov_b32_e32 v37, v147
	v_mov_b32_e32 v38, v148
	v_mov_b32_e32 v39, v149
	v_mov_b32_e32 v40, v150
	v_mov_b32_e32 v41, v151
	v_mov_b32_e32 v42, v152
	v_mov_b32_e32 v43, v153
	v_mov_b32_e32 v44, v154
	v_mov_b32_e32 v45, v155
	v_mov_b32_e32 v46, v156
	v_mov_b32_e32 v47, v157
	v_mov_b32_e32 v48, v158
	v_mov_b32_e32 v49, v159
	v_mov_b32_e32 v50, v160
	v_mov_b32_e32 v51, v161
	v_mov_b32_e32 v52, v162
	v_mov_b32_e32 v53, v163
	v_mov_b32_e32 v54, v164
	v_mov_b32_e32 v55, v165
	v_mov_b32_e32 v56, v166
	v_mov_b32_e32 v57, v167
	v_mov_b32_e32 v58, v168
	v_mov_b32_e32 v59, v169
	v_mov_b32_e32 v60, v170
	v_mov_b32_e32 v61, v171
	v_mov_b32_e32 v62, v172
	v_mov_b32_e32 v63, v173
	v_mov_b32_e32 v64, v174
	v_mov_b32_e32 v65, v175
	v_add_u32_e32 v176, s60, v108
	v_cmp_ge_i32_e64 s[30:31], s38, v176
	s_and_saveexec_b64 s[100:101], s[30:31]
	s_cbranch_execz .Lmy_w_pfend
	v_mul_hi_i32 v112, v176, s5
	v_lshrrev_b32_e32 v113, 31, v112
	v_ashrrev_i32_e32 v112, 7, v112
	v_add_u32_e32 v112, v112, v113
	v_mul_i32_i24_e32 v113, 0xfffffeed, v112
	v_add_lshl_u32 v188, v113, v176, 6
	v_lshlrev_b32_e32 v190, 6, v112
	v_or_b32_e32 v112, v188, v66
	v_ashrrev_i32_e32 v189, 31, v188
	v_cmp_gt_i32_e64 s[14:15], s33, v112
	v_or_b32_e32 v191, v190, v93
	v_lshl_add_u64 v[192:193], v[188:189], 2, v[84:85]
	v_mov_b32_e32 v112, 0
	v_mov_b32_e32 v116, 0
	v_mov_b32_e32 v117, 0
	v_mov_b32_e32 v118, 0
	v_mov_b32_e32 v119, 0
	s_and_saveexec_b64 s[28:29], s[14:15]
	s_cbranch_execz .Lmy_wb_12
	v_mad_i64_i32 v[114:115], s[30:31], v191, s36, v[192:193]
	global_load_dwordx4 v[116:119], v[114:115], off

; #define LAS __attribute__((address_space(3)))
; __device__ __forceinline__ unsigned cvt_pk_bf16(float lo, float hi) { unsigned r; asm volatile("s_nop 0\n\tv_cvt_pk_bf16_f32 %0, %1, %2" : "=v"(r) : "v"(lo), "v"(hi)); return r; }
; #define LDS_FENCE() asm volatile("s_waitcnt lgkmcnt(0)" ::: "memory")
; __device__ __forceinline__ void tr_item(const float* W, int K, int N, bf16_t* WT, int ldk, int split, int shift, LAS float* scr, int item, int lane) {
;     ...
;     for (int i = 0; i < 16; ++i) { const int kk = i * 4 + rq; tv[i] = okc ? *(const f32x4*)(W + (size_t)(k0 + kk) * N + n0 + c4) : (f32x4){0.f, 0.f, 0.f, 0.f}; }
; #pragma unroll
;     for (int i = 0; i < 16; ++i) { const int kk = i * 4 + rq; LAS float* d = scr + kk * 65 + c4; d[0] = tv[i][0]; d[1] = tv[i][1]; d[2] = tv[i][2]; d[3] = tv[i][3]; }
;     LDS_FENCE();
;     const int c = lane & 7;
; #pragma unroll
;     for (int j = 0; j < 8; ++j) { const int n = (lane >> 3) + 8 * j, ng = n0 + n;
;         if (ng < N) { const LAS float* sp = scr + (8 * c) * 65 + n;
;             u32x4 o; o.x = cvt_pk_bf16(sp[0], sp[65]); o.y = cvt_pk_bf16(sp[130], sp[195]); o.z = cvt_pk_bf16(sp[260], sp[325]); o.w = cvt_pk_bf16(sp[390], sp[455]);
;             const int dr = ng < split ? ng : ng + shift;
;             *(u32x4*)(WT + (size_t)dr * ldk + k0 + 8 * c) = o; } }
.Lmy_w_pfend:
	s_or_b64 exec, exec, s[100:101]
	ds_write2_b32 v94, v6, v7 offset1:1
	ds_write2_b32 v94, v8, v9 offset0:2 offset1:3
	v_add_u32_e32 v6, 0x410, v94
	ds_write2_b32 v6, v2, v3 offset1:1
	v_add_u32_e32 v2, 0x418, v94
	ds_write2_b32 v2, v4, v5 offset1:1
	v_add_u32_e32 v2, 0x820, v94
	ds_write2_b32 v2, v14, v15 offset1:1
	v_add_u32_e32 v2, 0x828, v94
	ds_write2_b32 v2, v16, v17 offset1:1
	v_add_u32_e32 v2, 0xc30, v94
	ds_write2_b32 v2, v10, v11 offset1:1
	v_add_u32_e32 v2, 0xc38, v94
	ds_write2_b32 v2, v12, v13 offset1:1
	v_add_u32_e32 v2, 0x1040, v94
	ds_write2_b32 v2, v22, v23 offset1:1
	v_add_u32_e32 v2, 0x1048, v94
	ds_write2_b32 v2, v24, v25 offset1:1
	v_add_u32_e32 v2, 0x1450, v94
	ds_write2_b32 v2, v18, v19 offset1:1
	v_add_u32_e32 v2, 0x1458, v94
	ds_write2_b32 v2, v20, v21 offset1:1
	v_add_u32_e32 v2, 0x1860, v94
	ds_write2_b32 v2, v30, v31 offset1:1
	v_add_u32_e32 v2, 0x1868, v94
	ds_write2_b32 v2, v32, v33 offset1:1
	v_add_u32_e32 v2, 0x1c70, v94
	ds_write2_b32 v2, v26, v27 offset1:1
	v_add_u32_e32 v2, 0x1c78, v94
	ds_write2_b32 v2, v28, v29 offset1:1
	v_add_u32_e32 v2, 0x2080, v94
	ds_write2_b32 v2, v38, v39 offset1:1
	v_add_u32_e32 v2, 0x2088, v94
	ds_write2_b32 v2, v40, v41 offset1:1
	v_add_u32_e32 v2, 0x2490, v94
	ds_write2_b32 v2, v34, v35 offset1:1
	v_add_u32_e32 v2, 0x2498, v94
	ds_write2_b32 v2, v36, v37 offset1:1
	v_add_u32_e32 v2, 0x28a0, v94
	ds_write2_b32 v2, v46, v47 offset1:1
	v_add_u32_e32 v2, 0x28a8, v94
	ds_write2_b32 v2, v48, v49 offset1:1
	v_add_u32_e32 v2, 0x2cb0, v94
	ds_write2_b32 v2, v42, v43 offset1:1
	v_add_u32_e32 v2, 0x2cb8, v94
	ds_write2_b32 v2, v44, v45 offset1:1
	v_add_u32_e32 v2, 0x30c0, v94
	ds_write2_b32 v2, v54, v55 offset1:1
	v_add_u32_e32 v2, 0x30c8, v94
	ds_write2_b32 v2, v56, v57 offset1:1
	v_add_u32_e32 v2, 0x34d0, v94
	ds_write2_b32 v2, v50, v51 offset1:1
	v_add_u32_e32 v2, 0x34d8, v94
	ds_write2_b32 v2, v52, v53 offset1:1
	v_add_u32_e32 v2, 0x38e0, v94
	ds_write2_b32 v2, v62, v63 offset1:1
	v_add_u32_e32 v2, 0x38e8, v94
	ds_write2_b32 v2, v64, v65 offset1:1
	v_add_u32_e32 v2, 0x3cf0, v94
	ds_write2_b32 v2, v58, v59 offset1:1
	v_add_u32_e32 v2, 0x3cf8, v94
	ds_write2_b32 v2, v60, v61 offset1:1
	s_waitcnt lgkmcnt(0)
	v_ashrrev_i32_e32 v89, 31, v88
	v_or_b32_e32 v4, v86, v95
	v_lshl_add_u64 v[2:3], v[88:89], 1, v[82:83]
	v_cmp_gt_i32_e64 s[14:15], s33, v4
	s_and_saveexec_b64 s[28:29], s[14:15]
	s_cbranch_execz .LBB0_44
	ds_read2_b32 v[6:7], v96 offset1:65
	s_waitcnt lgkmcnt(0)
	s_nop 0
	v_cvt_pk_bf16_f32 v6, v6, v7
	ds_read2_b32 v[8:9], v96 offset0:130 offset1:195
	v_add_u32_e32 v5, 0x400, v96
	s_waitcnt lgkmcnt(0)
	s_nop 0
	v_cvt_pk_bf16_f32 v7, v8, v9
	ds_read2_b32 v[8:9], v5 offset0:4 offset1:69
	v_cmp_gt_i32_e64 s[14:15], s37, v4
	s_waitcnt lgkmcnt(0)
	s_nop 0
	v_cvt_pk_bf16_f32 v8, v8, v9
	ds_read2_b32 v[10:11], v5 offset0:134 offset1:199
	s_waitcnt lgkmcnt(0)
	s_nop 0
	v_cvt_pk_bf16_f32 v9, v10, v11
	v_cndmask_b32_e64 v5, v106, 0, s[14:15]
	v_add_u32_e32 v4, v5, v4
	v_ashrrev_i32_e32 v5, 31, v4
	v_lshlrev_b64 v[4:5], 12, v[4:5]
	v_lshl_add_u64 v[4:5], v[2:3], 0, v[4:5]
	global_store_dwordx4 v[4:5], v[6:9], off
